# diff tile loop head aligned to 64 bytes (was at an offset of 4 mod 8)
# speedup vs baseline: 1.0085x; 1.0085x over previous
; #define ATT_WAIT_BAR(pending) do { if (pending) { if (FOX) asm volatile("s_waitcnt vmcnt(5) lgkmcnt(0)\n\ts_barrier" ::: "memory"); else asm volatile("s_waitcnt vmcnt(4) lgkmcnt(0)\n\ts_barrier" ::: "memory"); } \
;         else asm volatile("s_waitcnt vmcnt(0) lgkmcnt(0)\n\ts_barrier" ::: "memory"); } while (0)
; template <bool FOX> ...
;     ...
;     int t = FOX ? NT : 1;
;     ATT_DMA(t, 0);
;     { const int t1_ = FOX ? t - 1 : t + 1; const bool h1_ = FOX ? (t1_ >= 1) : (t1_ <= NT); if (h1_) ATT_DMA(t1_, 1); ATT_WAIT_BAR(h1_); }
;     bool wmore = (tq >= 1), first = true;
;     float mref = 0.f;
;     f32x16 negm;
; #pragma unroll
;     for (int r = 0; r < 16; ++r) negm[r] = 0.f;
;     bf16x8 pf[4];
; #pragma unroll
;     for (int s = 0; s < 4; ++s) pf[s] = (bf16x8){0, 0, 0, 0, 0, 0, 0, 0};
;     ...
;     int pbuf = 0, buf = 0;
.Ldiff_noprio:
	s_lshl_b32 s7, s22, 1
	s_mov_b32 s6, 1
	s_mov_b32 s23, 0
	s_sub_i32 s18, 0, s7
	s_movk_i32 s19, 0xff80
	s_movk_i32 s16, 0x100
	v_mov_b32_e32 v97, v96
	v_mov_b32_e32 v98, v96
	v_mov_b32_e32 v99, v96
	v_mov_b32_e32 v100, v96
	v_mov_b32_e32 v101, v96
	v_mov_b32_e32 v102, v96
	v_mov_b32_e32 v103, v96
	v_mov_b32_e32 v104, v96
	v_mov_b32_e32 v105, v96
	v_mov_b32_e32 v106, v96
	v_mov_b32_e32 v107, v96
	v_mov_b32_e32 v108, v96
	v_mov_b32_e32 v109, v96
	v_mov_b32_e32 v110, v96
	v_mov_b32_e32 v111, v96
	.p2align	6
